# prompt GLA output item: dv rows of the MFMA A operands permuted so a lane's two result blocks are contiguous; gate loads widened to 16 B per lane
# baseline (speedup 1.0000x reference)
; template <bool SMP>
; __device__ __forceinline__ void gla_out_item(const Params& p, int l, int c, int h, LAS unsigned char* lds) {
;     ...
;     const int t8 = tid >> 3, dg = (tid & 7) * 16;
;     u32x4 qw0, qw1, kw0, kw1, ew0, ew1;
;     if (!SMP) {
;         const size_t ro = (size_t)(tok0 + t8) * 512 + h * 128 + dg;
;         qw0 = *(const u32x4*)((const u16*)(ws + WS_ZQ) + ro); qw1 = *(const u32x4*)((const u16*)(ws + WS_ZQ) + ro + 8);
;         kw0 = *(const u32x4*)((const u16*)(ws + WS_ZK) + ro); kw1 = *(const u32x4*)((const u16*)(ws + WS_ZK) + ro + 8);
;         ew0 = *(const u32x4*)((const u16*)(ws + WS_BCUM) + ro); ew1 = *(const u32x4*)((const u16*)(ws + WS_BCUM) + ro + 8);
;     } else {
; #pragma unroll
;         for (int i = 0; i < 16; ++i) { qraw[i] = qp[i * 512]; kraw[i] = kp[i * 512]; }
;     }
;     const u16* vt = (const u16*)(ws + WS_ZVT) + (size_t)(h * 256 + w * 32 + fr) * T + tok0 + fq * 8;
;     bf16x8 bv[2][2];
; #pragma unroll
;     for (int kk = 0; kk < 2; ++kk)
; #pragma unroll
;         for (int n = 0; n < 2; ++n) bv[kk][n] = *(const bf16x8*)(vt + (size_t)(n * 16) * T + kk * 32);
;     const u16* sp = (const u16*)(ws + WS_SP) + (size_t)(c * 4 + h) * 32768 + (size_t)(w * 32 + fr) * 128 + fq * 8;
;     bf16x8 bs[4][2];
;     if (!SMP) {
; #pragma unroll
;         for (int kk = 0; kk < 4; ++kk)
; #pragma unroll
;             for (int n = 0; n < 2; ++n) bs[kk][n] = *(const bf16x8*)(sp + n * 16 * 128 + kk * 32);
;     } else {
;         const float* s0 = p.state_gla + (((size_t)l * 8 + (c - 256)) * 4 + h) * 32768 + w * 32 + fr;
; #pragma unroll
;         for (int kk = 0; kk < 4; ++kk)
; #pragma unroll
;             for (int n = 0; n < 2; ++n) {
;                 float sv[8];
; #pragma unroll
;                 for (int j = 0; j < 8; ++j) sv[j] = s0[(size_t)(kk * 32 + fq * 8 + j) * 256 + n * 16];
;                 u32x4 pw; pw.x = cvt_pk_bf16(sv[0], sv[1]); pw.y = cvt_pk_bf16(sv[2], sv[3]); pw.z = cvt_pk_bf16(sv[4], sv[5]); pw.w = cvt_pk_bf16(sv[6], sv[7]);
;                 bs[kk][n] = __builtin_bit_cast(bf16x8, pw);
;             }
;     }
;     u32x2 gav[4][2];
; #pragma unroll
;     for (int mt = 0; mt < 4; ++mt)
; #pragma unroll
;         for (int n = 0; n < 2; ++n) gav[mt][n] = *(const u32x2*)((const u16*)(ws + WS_ZGA) + (size_t)(tok0 + mt * 16 + fr) * 1024 + h * 256 + w * 32 + n * 16 + fq * 4);
.LBB0_663:
	s_and_b64 vcc, exec, s[0:1]
	s_cbranch_vccz .LBB0_784
	s_add_i32 s0, s23, 0xfffffc18
	v_mov_b32_e32 v91, v200
	s_lshl_b32 s1, s0, 4
	s_and_b32 s10, s1, 0xffffffc0
	v_ashrrev_i32_e32 v106, 3, v91
	s_waitcnt lgkmcnt(0)
	v_add_u32_e32 v2, s10, v106
	s_and_b32 s7, s23, 3
	v_lshlrev_b32_e32 v0, 4, v91
	v_ashrrev_i32_e32 v3, 31, v2
	s_lshl_b32 s1, s7, 7
	v_and_b32_e32 v107, 0x70, v0
	v_lshlrev_b64 v[2:3], 9, v[2:3]
	v_or3_b32 v2, v2, s1, v107
	v_readlane_b32 s16, v253, 8
	v_lshlrev_b64 v[2:3], 1, v[2:3]
	v_readlane_b32 s17, v253, 9
	s_mov_b32 s2, s31
	v_ashrrev_i32_e32 v93, 6, v91
	v_lshl_add_u64 v[4:5], s[16:17], 0, v[2:3]
	v_readlane_b32 s16, v254, 34
	v_readlane_b32 s17, v254, 35
	s_lshl_b32 s6, s7, 8
	v_lshlrev_b32_e32 v86, 5, v93
	v_lshl_add_u64 v[6:7], s[16:17], 0, v[2:3]
	global_load_dwordx4 v[58:61], v[6:7], off offset:16
	global_load_dwordx4 v[94:97], v[6:7], off
	global_load_dwordx4 v[54:57], v[4:5], off offset:16
	global_load_dwordx4 v[98:101], v[4:5], off
	v_readlane_b32 s16, v254, 32
	v_readlane_b32 s17, v254, 33
	v_and_b32_e32 v90, 15, v91
	v_and_b32_e32 v114, 12, v90
	v_lshlrev_b32_e32 v114, 1, v114
	v_and_or_b32 v114, v90, 3, v114
	v_or_b32_e32 v114, 4, v114
	v_add_u32_e32 v0, s6, v86
	v_lshl_add_u64 v[2:3], s[16:17], 0, v[2:3]
	global_load_dwordx4 v[50:53], v[2:3], off offset:16
	global_load_dwordx4 v[102:105], v[2:3], off
	v_or_b32_e32 v0, v0, v114
	v_mov_b64_e32 v[2:3], s[26:27]
	v_bfe_u32 v92, v91, 4, 2
	v_mad_i64_i32 v[2:3], s[16:17], v0, s96, v[2:3]
	s_ashr_i32 s11, s10, 31
	v_lshl_add_u64 v[2:3], s[10:11], 1, v[2:3]
	v_lshlrev_b32_e32 v88, 4, v92
	v_mov_b32_e32 v89, v1
	v_lshl_add_u64 v[2:3], v[2:3], 0, v[88:89]
	s_mov_b32 s1, 0xfffdf000
	v_add_co_u32_e32 v4, vcc, s1, v2
	s_ashr_i32 s1, s0, 31
	s_nop 0
	v_addc_co_u32_e32 v5, vcc, -1, v3, vcc
	global_load_dwordx4 v[42:45], v[2:3], off
	global_load_dwordx4 v[26:29], v[2:3], off offset:64
	global_load_dwordx4 v[46:49], v[4:5], off
	global_load_dwordx4 v[30:33], v[4:5], off offset:64
	s_lshl_b64 s[0:1], s[0:1], 16
	v_readlane_b32 s11, v254, 47
	v_or_b32_e32 v2, v86, v114
	s_add_u32 s0, s11, s0
	v_readlane_b32 s11, v254, 48
	v_ashrrev_i32_e32 v3, 31, v2
	s_addc_u32 s1, s11, s1
	v_lshlrev_b64 v[2:3], 8, v[2:3]
	v_lshl_add_u64 v[2:3], s[0:1], 0, v[2:3]
	s_lshl_b32 s0, s7, 9
	v_readlane_b32 s1, v254, 49
	v_or_b32_e32 v84, s10, v90
	s_add_u32 s0, s1, s0
	v_readlane_b32 s1, v254, 50
	s_addc_u32 s1, s1, 0
	v_ashrrev_i32_e32 v87, 31, v86
	v_or_b32_e32 v78, 16, v84
	v_lshlrev_b32_e32 v0, 4, v92
	v_lshl_add_u64 v[2:3], v[2:3], 0, v[88:89]
	v_lshl_add_u64 v[62:63], v[86:87], 1, s[0:1]
	v_ashrrev_i32_e32 v85, 31, v84
	v_ashrrev_i32_e32 v79, 31, v78
	v_add_co_u32_e32 v6, vcc, 0xfffffc00, v2
	v_lshl_add_u64 v[62:63], v[62:63], 0, v[0:1]
	v_lshlrev_b64 v[64:65], 11, v[84:85]
	v_lshlrev_b64 v[66:67], 11, v[78:79]
	v_addc_co_u32_e32 v7, vcc, -1, v3, vcc
	v_lshl_add_u64 v[64:65], v[62:63], 0, v[64:65]
	v_lshl_add_u64 v[66:67], v[62:63], 0, v[66:67]
	global_load_dwordx4 v[34:37], v[2:3], off
	global_load_dwordx4 v[18:21], v[2:3], off offset:64
	global_load_dwordx4 v[38:41], v[6:7], off
	global_load_dwordx4 v[22:25], v[6:7], off offset:64
	global_load_dwordx4 v[10:13], v[2:3], off offset:128
	s_nop 0
	global_load_dwordx4 v[2:5], v[2:3], off offset:192
	s_nop 0
	global_load_dwordx4 v[14:17], v[6:7], off offset:128
	s_nop 0
	global_load_dwordx4 v[6:9], v[6:7], off offset:192
	s_nop 0
	global_load_dwordx4 v[80:83], v[64:65], off
	global_load_dwordx4 v[74:77], v[66:67], off
	v_or_b32_e32 v72, 32, v84
	v_or_b32_e32 v66, 48, v84
	v_ashrrev_i32_e32 v73, 31, v72
	v_ashrrev_i32_e32 v67, 31, v66
	v_lshlrev_b64 v[64:65], 11, v[72:73]
	v_lshlrev_b64 v[68:69], 11, v[66:67]
	v_lshl_add_u64 v[64:65], v[62:63], 0, v[64:65]
	v_lshl_add_u64 v[62:63], v[62:63], 0, v[68:69]
	global_load_dwordx4 v[68:71], v[64:65], off
	s_nop 0
	global_load_dwordx4 v[62:65], v[62:63], off
	s_nop 0
	s_waitcnt vmcnt(20)
	v_lshlrev_b32_e32 v0, 16, v94
	v_and_b32_e32 v89, 0xffff0000, v94
	s_waitcnt vmcnt(18)
	v_lshlrev_b32_e32 v94, 16, v98
	v_and_b32_e32 v98, 0xffff0000, v98
	v_mul_f32_e32 v94, 0x3db504f3, v94
	v_mul_f32_e32 v98, 0x3db504f3, v98
	v_mul_f32_e32 v94, v94, v0
	v_rcp_f32_e32 v0, v0
	v_mul_f32_e32 v98, v98, v89
	v_rcp_f32_e32 v89, v89
	s_waitcnt vmcnt(16)
; #define LAS __attribute__((address_space(3)))
; __device__ __forceinline__ unsigned cvt_pk_bf16(float lo, float hi) { unsigned r; asm("v_cvt_pk_bf16_f32 %0, %1, %2" : "=v"(r) : "v"(lo), "v"(hi)); return r; }
; __device__ __forceinline__ float bflo(unsigned w) { return __uint_as_float(w << 16); }
; __device__ __forceinline__ float bfhi(unsigned w) { return __uint_as_float(w & 0xffff0000u); }
; template <bool SMP>
; __device__ __forceinline__ void gla_out_item(const Params& p, int l, int c, int h, LAS unsigned char* lds) {
;     ...
;         const unsigned qq[8] = {qw0.x, qw0.y, qw0.z, qw0.w, qw1.x, qw1.y, qw1.z, qw1.w};
;         const unsigned kk8[8] = {kw0.x, kw0.y, kw0.z, kw0.w, kw1.x, kw1.y, kw1.z, kw1.w};
;         const unsigned ee[8] = {ew0.x, ew0.y, ew0.z, ew0.w, ew1.x, ew1.y, ew1.z, ew1.w};
;         unsigned qo[8], ko[8];
; #pragma unroll
;         for (int j = 0; j < 8; ++j) {
;             const float e0 = bflo(ee[j]), e1 = bfhi(ee[j]);
;             const float q0 = bflo(qq[j]) * 0.08838834764831845f * e0, q1 = bfhi(qq[j]) * 0.08838834764831845f * e1;
;             const float k0 = bflo(kk8[j]) * __builtin_amdgcn_rcpf(e0), k1 = bfhi(kk8[j]) * __builtin_amdgcn_rcpf(e1);
;             qo[j] = cvt_pk_bf16(q0, q1); ko[j] = cvt_pk_bf16(k0, k1);
;         }
;         u32x4 w0, w1; w0.x = qo[0]; w0.y = qo[1]; w0.z = qo[2]; w0.w = qo[3]; w1.x = qo[4]; w1.y = qo[5]; w1.z = qo[6]; w1.w = qo[7];
;         *(LAS u32x4*)(Q + t8 * 272 + dg * 2) = w0; *(LAS u32x4*)(Q + t8 * 272 + dg * 2 + 16) = w1;
;         w0.x = ko[0]; w0.y = ko[1]; w0.z = ko[2]; w0.w = ko[3]; w1.x = ko[4]; w1.y = ko[5]; w1.z = ko[6]; w1.w = ko[7];
;         *(LAS u32x4*)(Kt + t8 * 272 + dg * 2) = w0; *(LAS u32x4*)(Kt + t8 * 272 + dg * 2 + 16) = w1;
;     }
;     __syncthreads();
;     {
;         const int mt = w >> 1;
; #pragma unroll
;         for (int j = 0; j < 2; ++j) {
;             const int nt = (w & 1) * 2 + j;
;             f32x4 s = (f32x4){0.f, 0.f, 0.f, 0.f};
;             if (nt <= mt) {
; #pragma unroll
;                 for (int kk = 0; kk < 4; ++kk) {
;                     const bf16x8 a = *(const LAS bf16x8*)(Q + (mt * 16 + fr) * 272 + (kk * 32 + fq * 8) * 2);
;                     const bf16x8 bq = *(const LAS bf16x8*)(Kt + (nt * 16 + fr) * 272 + (kk * 32 + fq * 8) * 2);
;                     s = __builtin_amdgcn_mfma_f32_16x16x32_bf16(a, bq, s, 0, 0, 0);
;                 }
	v_lshlrev_b32_e32 v108, 16, v102
	v_and_b32_e32 v102, 0xffff0000, v102
	v_mul_f32_e32 v0, v0, v108
	v_mul_f32_e32 v89, v89, v102
	v_cvt_pk_bf16_f32 v94, v94, v98
	v_cvt_pk_bf16_f32 v98, v0, v89
	v_lshlrev_b32_e32 v0, 16, v95
	v_and_b32_e32 v89, 0xffff0000, v95
	v_lshlrev_b32_e32 v95, 16, v99
	v_mul_f32_e32 v95, 0x3db504f3, v95
	v_and_b32_e32 v99, 0xffff0000, v99
	v_mul_f32_e32 v95, v95, v0
	v_mul_f32_e32 v99, 0x3db504f3, v99
	v_rcp_f32_e32 v0, v0
	v_mul_f32_e32 v99, v99, v89
	v_rcp_f32_e32 v89, v89
	v_lshlrev_b32_e32 v102, 16, v103
	v_mul_f32_e32 v0, v0, v102
	v_and_b32_e32 v102, 0xffff0000, v103
	v_mul_f32_e32 v89, v89, v102
	v_cvt_pk_bf16_f32 v95, v95, v99
	v_cvt_pk_bf16_f32 v99, v0, v89
	v_lshlrev_b32_e32 v0, 16, v96
	v_and_b32_e32 v89, 0xffff0000, v96
	v_lshlrev_b32_e32 v96, 16, v100
	v_mul_f32_e32 v96, 0x3db504f3, v96
	v_and_b32_e32 v100, 0xffff0000, v100
	v_mul_f32_e32 v96, v96, v0
	v_mul_f32_e32 v100, 0x3db504f3, v100
	v_rcp_f32_e32 v0, v0
	v_mul_f32_e32 v100, v100, v89
	v_rcp_f32_e32 v89, v89
	v_lshlrev_b32_e32 v102, 16, v104
	v_mul_f32_e32 v0, v0, v102
	v_and_b32_e32 v102, 0xffff0000, v104
	v_mul_f32_e32 v89, v89, v102
	v_cvt_pk_bf16_f32 v96, v96, v100
	v_cvt_pk_bf16_f32 v100, v0, v89
	v_lshlrev_b32_e32 v0, 16, v97
	v_and_b32_e32 v89, 0xffff0000, v97
	v_lshlrev_b32_e32 v97, 16, v101
	v_mul_f32_e32 v97, 0x3db504f3, v97
	v_and_b32_e32 v101, 0xffff0000, v101
	v_mul_f32_e32 v97, v97, v0
	v_mul_f32_e32 v101, 0x3db504f3, v101
	v_rcp_f32_e32 v0, v0
	v_mul_f32_e32 v101, v101, v89
	v_rcp_f32_e32 v89, v89
	v_lshlrev_b32_e32 v102, 16, v105
	v_mul_f32_e32 v0, v0, v102
	v_and_b32_e32 v102, 0xffff0000, v105
	v_mul_f32_e32 v89, v89, v102
	v_cvt_pk_bf16_f32 v97, v97, v101
	v_cvt_pk_bf16_f32 v101, v0, v89
	v_lshlrev_b32_e32 v89, 16, v54
	v_and_b32_e32 v54, 0xffff0000, v54
	v_lshlrev_b32_e32 v0, 16, v58
	v_and_b32_e32 v58, 0xffff0000, v58
	v_mul_f32_e32 v89, 0x3db504f3, v89
	v_mul_f32_e32 v54, 0x3db504f3, v54
	v_mul_f32_e32 v89, v89, v0
	v_rcp_f32_e32 v0, v0
	v_mul_f32_e32 v54, v54, v58
	v_rcp_f32_e32 v58, v58
	v_lshlrev_b32_e32 v102, 16, v50
	v_and_b32_e32 v50, 0xffff0000, v50
	v_mul_f32_e32 v0, v0, v102
	v_mul_f32_e32 v58, v58, v50
	v_cvt_pk_bf16_f32 v50, v89, v54
	v_cvt_pk_bf16_f32 v54, v0, v58
	v_lshlrev_b32_e32 v0, 16, v59
	v_and_b32_e32 v58, 0xffff0000, v59
	v_lshlrev_b32_e32 v59, 16, v55
	v_and_b32_e32 v55, 0xffff0000, v55
	v_mul_f32_e32 v59, 0x3db504f3, v59
	v_mul_f32_e32 v55, 0x3db504f3, v55
	v_mul_f32_e32 v59, v59, v0
	v_rcp_f32_e32 v0, v0
	v_mul_f32_e32 v55, v55, v58
	v_rcp_f32_e32 v58, v58
	v_lshlrev_b32_e32 v89, 16, v51
	v_and_b32_e32 v51, 0xffff0000, v51
	v_mul_f32_e32 v0, v0, v89
	v_mul_f32_e32 v58, v58, v51
	v_cvt_pk_bf16_f32 v51, v59, v55
	v_lshlrev_b32_e32 v59, 16, v56
	v_and_b32_e32 v56, 0xffff0000, v56
	v_cvt_pk_bf16_f32 v55, v0, v58
	v_lshlrev_b32_e32 v0, 16, v60
	v_and_b32_e32 v58, 0xffff0000, v60
	v_mul_f32_e32 v59, 0x3db504f3, v59
	v_mul_f32_e32 v56, 0x3db504f3, v56
	v_mul_f32_e32 v59, v59, v0
	v_rcp_f32_e32 v0, v0
	v_mul_f32_e32 v56, v56, v58
	v_rcp_f32_e32 v58, v58
	v_lshlrev_b32_e32 v60, 16, v52
	v_and_b32_e32 v52, 0xffff0000, v52
	v_mul_f32_e32 v0, v0, v60
	v_mul_f32_e32 v58, v58, v52
	v_cvt_pk_bf16_f32 v52, v59, v56
	v_lshlrev_b32_e32 v59, 16, v57
	v_and_b32_e32 v57, 0xffff0000, v57
	v_cvt_pk_bf16_f32 v56, v0, v58
	v_lshlrev_b32_e32 v0, 16, v61
	v_and_b32_e32 v58, 0xffff0000, v61
	v_mul_f32_e32 v59, 0x3db504f3, v59
	v_mul_f32_e32 v57, 0x3db504f3, v57
	v_mul_f32_e32 v59, v59, v0
	v_rcp_f32_e32 v0, v0
	v_mul_f32_e32 v57, v57, v58
	v_rcp_f32_e32 v58, v58
	v_lshlrev_b32_e32 v60, 16, v53
	v_and_b32_e32 v53, 0xffff0000, v53
	v_mul_f32_e32 v0, v0, v60
	v_mul_f32_e32 v58, v58, v53
	v_cvt_pk_bf16_f32 v53, v59, v57
	v_cvt_pk_bf16_f32 v57, v0, v58
	v_mul_lo_u32 v0, v106, s30
	v_lshlrev_b32_e32 v58, 1, v107
	v_add3_u32 v0, 0, v0, v58
	ds_write_b128 v0, v[94:97] offset:4096
	ds_write_b128 v0, v[50:53] offset:4112
	ds_write_b128 v0, v[98:101] offset:21504
	ds_write_b128 v0, v[54:57] offset:21520
	v_ashrrev_i32_e32 v51, 7, v91
	v_lshlrev_b32_e32 v0, 1, v93
	v_lshlrev_b32_e32 v58, 4, v51
	v_and_b32_e32 v57, 2, v0
	v_or_b32_e32 v0, v58, v90
	v_mul_lo_u32 v0, v0, s30
	v_add_u32_e32 v0, 0, v0
	v_cmp_le_i32_e32 vcc, v57, v51
	v_lshl_or_b32 v59, v57, 4, v90
	v_mov_b32_e32 v50, 0
	v_add_u32_e32 v0, v0, v88
	v_mov_b32_e32 v52, 0
	v_mov_b32_e32 v53, 0
	v_mov_b32_e32 v54, 0
	v_mov_b32_e32 v55, 0
	s_waitcnt lgkmcnt(0)
	s_barrier
	s_and_saveexec_b64 s[0:1], vcc
	s_cbranch_execz .LBB0_666
	ds_read_b128 v[52:55], v0 offset:4096
	v_mul_u32_u24_e32 v56, 0x110, v59
	v_add3_u32 v56, 0, v56, v88
	ds_read_b128 v[94:97], v56 offset:21504
	s_waitcnt lgkmcnt(0)
	v_mfma_f32_16x16x32_bf16 v[52:55], v[52:55], v[94:97], 0
	ds_read_b128 v[94:97], v0 offset:4160
	ds_read_b128 v[98:101], v56 offset:21568
	s_waitcnt lgkmcnt(0)
	v_mfma_f32_16x16x32_bf16 v[52:55], v[94:97], v[98:101], v[52:55]
	ds_read_b128 v[94:97], v0 offset:4224
	ds_read_b128 v[98:101], v56 offset:21632
	s_waitcnt lgkmcnt(0)
	v_mfma_f32_16x16x32_bf16 v[52:55], v[94:97], v[98:101], v[52:55]
	ds_read_b128 v[94:97], v0 offset:4288
	ds_read_b128 v[98:101], v56 offset:21696
	s_waitcnt lgkmcnt(0)
	v_mfma_f32_16x16x32_bf16 v[52:55], v[94:97], v[98:101], v[52:55]

; #define LAS __attribute__((address_space(3)))
; __device__ __forceinline__ u16 f2bf(float f) { return (u16)(cvt_pk_bf16(f, 0.f) & 0xffffu); }
; template <bool SMP>
; __device__ __forceinline__ void gla_out_item(const Params& p, int l, int c, int h, LAS unsigned char* lds) {
;     ...
;             for (int e = 0; e < 4; ++e) { const int t = mt * 16 + fq * 4 + e, si = nt * 16 + fr; ((LAS u16*)P)[t * 72 + si] = f2bf(si <= t ? s[e] : 0.f); }
;         }
;     }
;     __syncthreads();
;     f32x4 o[4][2];
; #pragma unroll
;     for (int mt = 0; mt < 4; ++mt) { o[mt][0] = (f32x4){0.f, 0.f, 0.f, 0.f}; o[mt][1] = (f32x4){0.f, 0.f, 0.f, 0.f}; }
; #pragma unroll
;     for (int kk = 0; kk < 2; ++kk) {
; #pragma unroll
;         for (int mt = 0; mt < 4; ++mt) {
;             if (2 * kk <= mt) {
;                 const bf16x8 a = *(const LAS bf16x8*)(P + (mt * 16 + fr) * 144 + (kk * 32 + fq * 8) * 2);
; #pragma unroll
;                 for (int n = 0; n < 2; ++n) o[mt][n] = __builtin_amdgcn_mfma_f32_16x16x32_bf16(bv[kk][n], a, o[mt][n], 0, 0, 0);
;             }
;         }
;     }
; #pragma unroll
;     for (int kk = 0; kk < 4; ++kk) {
; #pragma unroll
;         for (int mt = 0; mt < 4; ++mt) {
;             const bf16x8 a = *(const LAS bf16x8*)(Q + (mt * 16 + fr) * 272 + (kk * 32 + fq * 8) * 2);
; #pragma unroll
;             for (int n = 0; n < 2; ++n) o[mt][n] = __builtin_amdgcn_mfma_f32_16x16x32_bf16(bs[kk][n], a, o[mt][n], 0, 0, 0);
;         }
;     }
; #pragma unroll
;     for (int mt = 0; mt < 4; ++mt) {
;         float s2 = 0.f;
; #pragma unroll
;         for (int n = 0; n < 2; ++n)
; #pragma unroll
;             for (int e = 0; e < 4; ++e) s2 += o[mt][n][e] * o[mt][n][e];
;         s2 += __shfl_xor(s2, 16); s2 += __shfl_xor(s2, 32);
;         if (fq == 0) red[w * 64 + mt * 16 + fr] = s2;
;     }
.LBB0_668:
	s_or_b64 exec, exec, s[0:1]
	v_cmp_le_i32_e32 vcc, v55, v60
	s_movk_i32 s0, 0x90
	s_nop 4
	v_cndmask_b32_e32 v0, 0, v50, vcc
	v_cvt_pk_bf16_f32 v0, v0, v1
	v_cmp_le_i32_e32 vcc, v55, v61
	ds_write_b16 v58, v0 offset:38944
	s_nop 0
	v_cndmask_b32_e32 v0, 0, v51, vcc
	v_cvt_pk_bf16_f32 v0, v0, v1
	v_cmp_le_i32_e32 vcc, v55, v89
	ds_write_b16 v58, v0 offset:39088
	s_nop 0
	v_cndmask_b32_e32 v0, 0, v52, vcc
	v_cvt_pk_bf16_f32 v0, v0, v1
	v_cmp_le_i32_e32 vcc, v55, v54
	ds_write_b16 v58, v0 offset:39232
	s_nop 0
	v_cndmask_b32_e32 v0, 0, v53, vcc
	v_cvt_pk_bf16_f32 v0, v0, v1
	ds_write_b16 v58, v0 offset:39376
	v_add_u32_e32 v0, 0, v88
	v_mad_u32_u24 v54, v90, s0, v0
	s_waitcnt lgkmcnt(0)
	s_barrier
	ds_read_b128 v[50:53], v54 offset:38912
	ds_read_b128 v[94:97], v54 offset:41216
	ds_read_b128 v[102:105], v54 offset:43520
	ds_read_b128 v[110:113], v54 offset:45824
	s_waitcnt vmcnt(15) lgkmcnt(3)
	v_mfma_f32_16x16x32_bf16 v[58:61], v[42:45], v[50:53], 0
	v_mad_u32_u24 v0, v90, s30, v0
	s_waitcnt vmcnt(13)
	v_mfma_f32_16x16x32_bf16 v[50:53], v[46:49], v[50:53], 0
	s_waitcnt lgkmcnt(2)
	v_mfma_f32_16x16x32_bf16 v[98:101], v[42:45], v[94:97], 0
	v_mfma_f32_16x16x32_bf16 v[94:97], v[46:49], v[94:97], 0
	s_waitcnt lgkmcnt(1)
	v_mfma_f32_16x16x32_bf16 v[106:109], v[42:45], v[102:105], 0
	v_mfma_f32_16x16x32_bf16 v[102:105], v[46:49], v[102:105], 0
	s_waitcnt lgkmcnt(0)
	v_mfma_f32_16x16x32_bf16 v[42:45], v[42:45], v[110:113], 0
	v_mfma_f32_16x16x32_bf16 v[46:49], v[46:49], v[110:113], 0
	ds_read_b128 v[110:113], v54 offset:43584
	s_waitcnt lgkmcnt(0)
	v_mfma_f32_16x16x32_bf16 v[106:109], v[26:29], v[110:113], v[106:109]
	s_waitcnt vmcnt(12)
	v_mfma_f32_16x16x32_bf16 v[102:105], v[30:33], v[110:113], v[102:105]
	ds_read_b128 v[110:113], v54 offset:45888
	s_waitcnt lgkmcnt(0)
	v_mfma_f32_16x16x32_bf16 v[26:29], v[26:29], v[110:113], v[42:45]
	s_nop 2
	ds_read_b128 v[42:45], v0 offset:4096
	v_mfma_f32_16x16x32_bf16 v[30:33], v[30:33], v[110:113], v[46:49]
	s_waitcnt vmcnt(11) lgkmcnt(0)
	v_mfma_f32_16x16x32_bf16 v[46:49], v[34:37], v[42:45], v[58:61]
	s_waitcnt vmcnt(9)
	v_mfma_f32_16x16x32_bf16 v[42:45], v[38:41], v[42:45], v[50:53]
	s_nop 2
	ds_read_b128 v[50:53], v0 offset:8448
	s_waitcnt lgkmcnt(0)
	v_mfma_f32_16x16x32_bf16 v[58:61], v[34:37], v[50:53], v[98:101]
	v_mfma_f32_16x16x32_bf16 v[50:53], v[38:41], v[50:53], v[94:97]
	s_nop 2
	ds_read_b128 v[94:97], v0 offset:12800
	s_waitcnt lgkmcnt(0)
	v_mfma_f32_16x16x32_bf16 v[98:101], v[34:37], v[94:97], v[106:109]
	v_mfma_f32_16x16x32_bf16 v[94:97], v[38:41], v[94:97], v[102:105]
	s_nop 2
	ds_read_b128 v[102:105], v0 offset:17152
	s_waitcnt lgkmcnt(0)
	v_mfma_f32_16x16x32_bf16 v[26:29], v[34:37], v[102:105], v[26:29]
	ds_read_b128 v[34:37], v0 offset:4160
	v_mfma_f32_16x16x32_bf16 v[30:33], v[38:41], v[102:105], v[30:33]
	s_waitcnt lgkmcnt(0)
	v_mfma_f32_16x16x32_bf16 v[38:41], v[18:21], v[34:37], v[46:49]
	s_waitcnt vmcnt(8)
	v_mfma_f32_16x16x32_bf16 v[34:37], v[22:25], v[34:37], v[42:45]
	s_nop 2
	ds_read_b128 v[42:45], v0 offset:8512
	s_waitcnt lgkmcnt(0)
	v_mfma_f32_16x16x32_bf16 v[46:49], v[18:21], v[42:45], v[58:61]
	v_mfma_f32_16x16x32_bf16 v[42:45], v[22:25], v[42:45], v[50:53]
	s_nop 2
	ds_read_b128 v[50:53], v0 offset:12864
	s_waitcnt lgkmcnt(0)
	v_mfma_f32_16x16x32_bf16 v[58:61], v[18:21], v[50:53], v[98:101]
	v_mfma_f32_16x16x32_bf16 v[50:53], v[22:25], v[50:53], v[94:97]
	s_nop 2
	ds_read_b128 v[94:97], v0 offset:17216
	s_waitcnt lgkmcnt(0)
	v_mfma_f32_16x16x32_bf16 v[18:21], v[18:21], v[94:97], v[26:29]
	s_nop 2
	ds_read_b128 v[26:29], v0 offset:4224
	v_mfma_f32_16x16x32_bf16 v[22:25], v[22:25], v[94:97], v[30:33]
	s_waitcnt vmcnt(7) lgkmcnt(0)
	v_mfma_f32_16x16x32_bf16 v[30:33], v[10:13], v[26:29], v[38:41]
	s_waitcnt vmcnt(5)
	v_mfma_f32_16x16x32_bf16 v[26:29], v[14:17], v[26:29], v[34:37]
	s_nop 2
	ds_read_b128 v[34:37], v0 offset:8576
	s_waitcnt lgkmcnt(0)
	v_mfma_f32_16x16x32_bf16 v[46:49], v[10:13], v[34:37], v[46:49]
	v_mfma_f32_16x16x32_bf16 v[42:45], v[14:17], v[34:37], v[42:45]
	ds_read_b128 v[34:37], v0 offset:12928
	s_waitcnt lgkmcnt(0)
	v_mfma_f32_16x16x32_bf16 v[58:61], v[10:13], v[34:37], v[58:61]
	v_mfma_f32_16x16x32_bf16 v[50:53], v[14:17], v[34:37], v[50:53]
	ds_read_b128 v[34:37], v0 offset:17280
	s_waitcnt lgkmcnt(0)
	v_mfma_f32_16x16x32_bf16 v[10:13], v[10:13], v[34:37], v[18:21]
	s_nop 2
	ds_read_b128 v[18:21], v0 offset:4288
	v_mfma_f32_16x16x32_bf16 v[14:17], v[14:17], v[34:37], v[22:25]
	s_waitcnt lgkmcnt(0)
	v_mfma_f32_16x16x32_bf16 v[38:41], v[2:5], v[18:21], v[30:33]
	s_waitcnt vmcnt(4)
	v_mfma_f32_16x16x32_bf16 v[34:37], v[6:9], v[18:21], v[26:29]
	ds_read_b128 v[18:21], v0 offset:8640
	s_waitcnt lgkmcnt(0)
	v_mfma_f32_16x16x32_bf16 v[30:33], v[2:5], v[18:21], v[46:49]
	v_mfma_f32_16x16x32_bf16 v[26:29], v[6:9], v[18:21], v[42:45]
	ds_read_b128 v[18:21], v0 offset:12992
	s_nop 1
	ds_read_b128 v[42:45], v0 offset:17344
	s_waitcnt lgkmcnt(1)
	v_mfma_f32_16x16x32_bf16 v[22:25], v[2:5], v[18:21], v[58:61]
	v_xor_b32_e32 v0, 16, v205
	v_mfma_f32_16x16x32_bf16 v[18:21], v[6:9], v[18:21], v[50:53]
	s_waitcnt lgkmcnt(0)
	v_mfma_f32_16x16x32_bf16 v[10:13], v[2:5], v[42:45], v[10:13]
	v_mfma_f32_16x16x32_bf16 v[2:5], v[6:9], v[42:45], v[14:17]
	v_and_b32_e32 v6, 64, v205
	v_add_u32_e32 v6, 64, v6
	v_cmp_lt_i32_e32 vcc, v0, v6
	v_xor_b32_e32 v7, 32, v205
	v_lshlrev_b32_e32 v8, 2, v90
	v_cndmask_b32_e32 v0, v205, v0, vcc
	v_cmp_lt_i32_e32 vcc, v7, v6
	v_lshlrev_b32_e32 v0, 2, v0
	s_nop 0
	v_cndmask_b32_e32 v6, v205, v7, vcc
	v_and_b32_e32 v7, 0x3fffffc0, v91
	v_lshlrev_b32_e32 v7, 2, v7
	v_add3_u32 v7, 0, v7, v8
	v_mul_f32_e32 v8, v39, v39
	v_fmac_f32_e32 v8, v38, v38
	v_fmac_f32_e32 v8, v40, v40
	v_fmac_f32_e32 v8, v41, v41
	v_fmac_f32_e32 v8, v34, v34
	v_fmac_f32_e32 v8, v35, v35
	v_fmac_f32_e32 v8, v36, v36
	v_fmac_f32_e32 v8, v37, v37
	ds_bpermute_b32 v9, v0, v8
	v_lshlrev_b32_e32 v6, 2, v6
	v_cmp_eq_u32_e32 vcc, 0, v92
	s_waitcnt lgkmcnt(0)
	v_add_f32_e32 v8, v8, v9
	ds_bpermute_b32 v9, v6, v8
	s_and_saveexec_b64 s[0:1], vcc
	s_cbranch_execz .LBB0_670
	s_waitcnt lgkmcnt(0)
	v_add_f32_e32 v8, v8, v9
	ds_write_b32 v7, v8 offset:2048

; __device__ __forceinline__ unsigned cvt_pk_bf16(float lo, float hi) { unsigned r; asm("v_cvt_pk_bf16_f32 %0, %1, %2" : "=v"(r) : "v"(lo), "v"(hi)); return r; }
; __device__ __forceinline__ float bflo(unsigned w) { return __uint_as_float(w << 16); }
; __device__ __forceinline__ float bfhi(unsigned w) { return __uint_as_float(w & 0xffff0000u); }
; __device__ __forceinline__ float silu(float x) { return x / (1.f + __expf(-x)); }
; template <bool SMP>
; __device__ __forceinline__ void gla_out_item(const Params& p, int l, int c, int h, LAS unsigned char* lds) {
;     ...
;     __syncthreads();
;     const float* gn = p.gla_norm_g + l * 256 + w * 32 + fq * 4;
;     const f32x4 g0 = *(const f32x4*)gn, g1 = *(const f32x4*)(gn + 16);
; #pragma unroll
;     for (int mt = 0; mt < 4; ++mt) {
;         const int t = mt * 16 + fr;
;         float tot = 0.f;
; #pragma unroll
;         for (int ww = 0; ww < 8; ++ww) tot += red[ww * 64 + t];
;         const float rs = rsqrtf(tot * (1.f / 256.f) + EPS);
; #pragma unroll
;         for (int n = 0; n < 2; ++n) {
;             const f32x4 gg = n ? g1 : g0; const u32x2 ga = gav[mt][n];
;             const float o0 = o[mt][n][0] * rs * gg[0] * silu(bflo(ga.x)), o1 = o[mt][n][1] * rs * gg[1] * silu(bfhi(ga.x));
;             const float o2 = o[mt][n][2] * rs * gg[2] * silu(bflo(ga.y)), o3 = o[mt][n][3] * rs * gg[3] * silu(bfhi(ga.y));
;             u32x2 wv; wv.x = cvt_pk_bf16(o0, o1); wv.y = cvt_pk_bf16(o2, o3);
;             *(u32x2*)((u16*)(ws + WS_OBUF) + (size_t)(tok0 + t) * 2048 + h * 256 + w * 32 + n * 16 + fq * 4) = wv;
;         }
.LBB0_676:
	s_or_b64 exec, exec, s[0:1]
	s_lshl_b32 s0, s2, 8
	s_ashr_i32 s1, s0, 31
	s_lshl_b64 s[0:1], s[0:1], 2
	s_add_u32 s0, s46, s0
	s_addc_u32 s1, s47, s1
	s_waitcnt lgkmcnt(0)
	v_lshl_add_u64 v[6:7], v[86:87], 2, s[0:1]
	v_lshlrev_b32_e32 v0, 3, v56
	v_lshl_add_u64 v[6:7], v[6:7], 0, v[0:1]
	s_barrier
	global_load_dwordx4 v[14:17], v[6:7], off offset:16
	s_nop 0
	global_load_dwordx4 v[6:9], v[6:7], off
	s_lshl_b32 s0, s6, 1
	v_readlane_b32 s1, v252, 25
	s_add_u32 s0, s1, s0
	v_readlane_b32 s1, v252, 26
	s_addc_u32 s1, s1, 0
	v_lshlrev_b32_e32 v0, 2, v56
	v_lshl_add_u64 v[42:43], v[86:87], 1, s[0:1]
	v_lshl_add_u64 v[42:43], v[42:43], 0, v[0:1]
	v_lshl_add_u32 v0, v90, 2, 0
	v_add_u32_e32 v86, 0x800, v0
	ds_read2_b32 v[44:45], v86 offset1:16
	ds_read2_b32 v[46:47], v86 offset0:64 offset1:80
	ds_read2_b32 v[48:49], v86 offset0:128 offset1:144
	ds_read2_b32 v[50:51], v86 offset0:192 offset1:208
	v_add_u32_e32 v0, 0xc00, v0
	ds_read2_b32 v[52:53], v0 offset1:16
	s_waitcnt lgkmcnt(4)
	v_add_f32_e32 v44, 0, v44
	ds_read2_b32 v[54:55], v0 offset0:64 offset1:80
	s_waitcnt lgkmcnt(4)
	v_add_f32_e32 v44, v44, v46
	ds_read2_b32 v[56:57], v0 offset0:128 offset1:144
	s_waitcnt lgkmcnt(4)
	v_add_f32_e32 v44, v44, v48
	ds_read2_b32 v[58:59], v0 offset0:192 offset1:208
	s_waitcnt lgkmcnt(4)
	v_add_f32_e32 v44, v44, v50
	s_waitcnt lgkmcnt(3)
	v_add_f32_e32 v44, v44, v52
	s_waitcnt lgkmcnt(2)
	v_add_f32_e32 v44, v44, v54
	s_waitcnt lgkmcnt(1)
	v_add_f32_e32 v44, v44, v56
	s_waitcnt lgkmcnt(0)
	v_add_f32_e32 v44, v44, v58
	v_fmamk_f32 v44, v44, 0x3b800000, v203
	v_cmp_gt_f32_e32 vcc, s89, v44
	v_mul_f32_e32 v46, 0x4b800000, v44
	v_lshlrev_b64 v[60:61], 12, v[84:85]
	v_cndmask_b32_e32 v44, v44, v46, vcc
	v_rsq_f32_e32 v44, v44
	v_lshl_add_u64 v[60:61], v[42:43], 0, v[60:61]
	v_mul_f32_e32 v46, 0x45800000, v44
	v_cndmask_b32_e32 v44, v44, v46, vcc
	s_waitcnt vmcnt(5)
	v_lshlrev_b32_e32 v46, 16, v82
	v_mul_f32_e32 v48, 0xbfb8aa3b, v46
	v_exp_f32_e32 v48, v48
	v_mul_f32_e32 v38, v38, v44
	v_mul_f32_e32 v39, v39, v44
	v_mul_f32_e32 v40, v40, v44
	v_add_f32_e32 v48, 1.0, v48
	v_div_scale_f32 v50, s[0:1], v48, v48, v46
	v_rcp_f32_e32 v52, v50
	v_mul_f32_e32 v41, v41, v44
	v_mul_f32_e32 v34, v34, v44
	v_mul_f32_e32 v35, v35, v44
	v_fma_f32 v54, -v50, v52, 1.0
	v_fmac_f32_e32 v52, v54, v52
	v_div_scale_f32 v54, vcc, v46, v48, v46
	v_mul_f32_e32 v56, v54, v52
	v_fma_f32 v58, -v50, v56, v54
	v_fmac_f32_e32 v56, v58, v52
	v_fma_f32 v50, -v50, v56, v54
	v_div_fmas_f32 v50, v50, v52, v56
	v_div_fixup_f32 v46, v50, v48, v46
	v_mul_f32_e32 v36, v36, v44
	v_mul_f32_e32 v37, v37, v44
	s_waitcnt vmcnt(1)
	v_mul_f32_e32 v38, v14, v38
	v_mul_f32_e32 v38, v46, v38
	v_and_b32_e32 v46, 0xffff0000, v82
	v_mul_f32_e32 v48, 0xbfb8aa3b, v46
	v_exp_f32_e32 v48, v48
	v_mul_f32_e32 v39, v15, v39
	v_mul_f32_e32 v40, v16, v40
	v_mul_f32_e32 v41, v17, v41
	v_add_f32_e32 v48, 1.0, v48
	v_div_scale_f32 v50, s[0:1], v48, v48, v46
	v_rcp_f32_e32 v52, v50
	s_waitcnt vmcnt(0)
	v_mul_f32_e32 v34, v6, v34
	v_mul_f32_e32 v35, v7, v35
	v_mul_f32_e32 v36, v8, v36
	v_fma_f32 v54, -v50, v52, 1.0
	v_fmac_f32_e32 v52, v54, v52
	v_div_scale_f32 v54, vcc, v46, v48, v46
	v_mul_f32_e32 v56, v54, v52
	v_fma_f32 v58, -v50, v56, v54
	v_fmac_f32_e32 v56, v58, v52
	v_fma_f32 v50, -v50, v56, v54
	v_div_fmas_f32 v50, v50, v52, v56
	v_div_fixup_f32 v46, v50, v48, v46
	v_mul_f32_e32 v39, v46, v39
	v_lshlrev_b32_e32 v46, 16, v83
	v_mul_f32_e32 v48, 0xbfb8aa3b, v46
	v_exp_f32_e32 v48, v48
	v_cvt_pk_bf16_f32 v38, v38, v39
	v_mul_f32_e32 v37, v9, v37
	v_add_f32_e32 v48, 1.0, v48
	v_div_scale_f32 v50, s[0:1], v48, v48, v46
	v_rcp_f32_e32 v52, v50
	s_nop 0
	v_fma_f32 v54, -v50, v52, 1.0
	v_fmac_f32_e32 v52, v54, v52
	v_div_scale_f32 v54, vcc, v46, v48, v46
	v_mul_f32_e32 v56, v54, v52
	v_fma_f32 v58, -v50, v56, v54
	v_fmac_f32_e32 v56, v58, v52
	v_fma_f32 v50, -v50, v56, v54
	v_div_fmas_f32 v50, v50, v52, v56
	v_div_fixup_f32 v46, v50, v48, v46
	v_mul_f32_e32 v40, v46, v40
	v_and_b32_e32 v46, 0xffff0000, v83
	v_mul_f32_e32 v48, 0xbfb8aa3b, v46
	v_exp_f32_e32 v48, v48
	s_nop 0
	v_add_f32_e32 v48, 1.0, v48
	v_div_scale_f32 v50, s[0:1], v48, v48, v46
	v_rcp_f32_e32 v52, v50
	s_nop 0
	v_fma_f32 v54, -v50, v52, 1.0
	v_fmac_f32_e32 v52, v54, v52
	v_div_scale_f32 v54, vcc, v46, v48, v46
	v_mul_f32_e32 v56, v54, v52
	v_fma_f32 v58, -v50, v56, v54
	v_fmac_f32_e32 v56, v58, v52
	v_fma_f32 v50, -v50, v56, v54
	v_div_fmas_f32 v50, v50, v52, v56
	v_div_fixup_f32 v46, v50, v48, v46
	v_mul_f32_e32 v41, v46, v41
	v_cvt_pk_bf16_f32 v39, v40, v41
	global_store_dwordx2 v[60:61], v[38:39], off offset:8
	v_lshlrev_b32_e32 v38, 16, v80
	v_mul_f32_e32 v39, 0xbfb8aa3b, v38
	v_exp_f32_e32 v39, v39
	s_nop 0
	v_add_f32_e32 v39, 1.0, v39
	v_div_scale_f32 v40, s[0:1], v39, v39, v38
	v_rcp_f32_e32 v41, v40
	s_nop 0
	v_fma_f32 v46, -v40, v41, 1.0
	v_fmac_f32_e32 v41, v46, v41
	v_div_scale_f32 v46, vcc, v38, v39, v38
	v_mul_f32_e32 v48, v46, v41
	v_fma_f32 v50, -v40, v48, v46
	v_fmac_f32_e32 v48, v50, v41
	v_fma_f32 v40, -v40, v48, v46
	v_div_fmas_f32 v40, v40, v41, v48
	v_div_fixup_f32 v38, v40, v39, v38
	v_mul_f32_e32 v34, v38, v34
	v_and_b32_e32 v38, 0xffff0000, v80
	v_mul_f32_e32 v39, 0xbfb8aa3b, v38
	v_exp_f32_e32 v39, v39
	s_nop 0
	v_add_f32_e32 v39, 1.0, v39
	v_div_scale_f32 v40, s[0:1], v39, v39, v38
	v_rcp_f32_e32 v41, v40
	s_nop 0
	v_fma_f32 v46, -v40, v41, 1.0
	v_fmac_f32_e32 v41, v46, v41
	v_div_scale_f32 v46, vcc, v38, v39, v38
	v_mul_f32_e32 v48, v46, v41
	v_fma_f32 v50, -v40, v48, v46
	v_fmac_f32_e32 v48, v50, v41
	v_fma_f32 v40, -v40, v48, v46
	v_div_fmas_f32 v40, v40, v41, v48
	v_div_fixup_f32 v38, v40, v39, v38
; __device__ __forceinline__ unsigned cvt_pk_bf16(float lo, float hi) { unsigned r; asm("v_cvt_pk_bf16_f32 %0, %1, %2" : "=v"(r) : "v"(lo), "v"(hi)); return r; }
; __device__ __forceinline__ float bflo(unsigned w) { return __uint_as_float(w << 16); }
; __device__ __forceinline__ float bfhi(unsigned w) { return __uint_as_float(w & 0xffff0000u); }
; __device__ __forceinline__ float silu(float x) { return x / (1.f + __expf(-x)); }
; template <bool SMP>
; __device__ __forceinline__ void gla_out_item(const Params& p, int l, int c, int h, LAS unsigned char* lds) {
;     ...
;     for (int mt = 0; mt < 4; ++mt) {
;         const int t = mt * 16 + fr;
;         float tot = 0.f;
; #pragma unroll
;         for (int ww = 0; ww < 8; ++ww) tot += red[ww * 64 + t];
;         const float rs = rsqrtf(tot * (1.f / 256.f) + EPS);
; #pragma unroll
;         for (int n = 0; n < 2; ++n) {
;             const f32x4 gg = n ? g1 : g0; const u32x2 ga = gav[mt][n];
;             const float o0 = o[mt][n][0] * rs * gg[0] * silu(bflo(ga.x)), o1 = o[mt][n][1] * rs * gg[1] * silu(bfhi(ga.x));
;             const float o2 = o[mt][n][2] * rs * gg[2] * silu(bflo(ga.y)), o3 = o[mt][n][3] * rs * gg[3] * silu(bfhi(ga.y));
;             u32x2 wv; wv.x = cvt_pk_bf16(o0, o1); wv.y = cvt_pk_bf16(o2, o3);
;             *(u32x2*)((u16*)(ws + WS_OBUF) + (size_t)(tok0 + t) * 2048 + h * 256 + w * 32 + n * 16 + fq * 4) = wv;
;         }
	v_mul_f32_e32 v35, v38, v35
	v_lshlrev_b32_e32 v38, 16, v81
	v_mul_f32_e32 v39, 0xbfb8aa3b, v38
	v_exp_f32_e32 v39, v39
	v_cvt_pk_bf16_f32 v34, v34, v35
	s_nop 0
	v_add_f32_e32 v39, 1.0, v39
	v_div_scale_f32 v40, s[0:1], v39, v39, v38
	v_rcp_f32_e32 v41, v40
	s_nop 0
	v_fma_f32 v46, -v40, v41, 1.0
	v_fmac_f32_e32 v41, v46, v41
	v_div_scale_f32 v46, vcc, v38, v39, v38
	v_mul_f32_e32 v48, v46, v41
	v_fma_f32 v50, -v40, v48, v46
	v_fmac_f32_e32 v48, v50, v41
	v_fma_f32 v40, -v40, v48, v46
	v_div_fmas_f32 v40, v40, v41, v48
	v_div_fixup_f32 v38, v40, v39, v38
	v_mul_f32_e32 v36, v38, v36
	v_and_b32_e32 v38, 0xffff0000, v81
	v_mul_f32_e32 v39, 0xbfb8aa3b, v38
	v_exp_f32_e32 v39, v39
	s_nop 0
	v_add_f32_e32 v39, 1.0, v39
	v_div_scale_f32 v40, s[0:1], v39, v39, v38
	v_rcp_f32_e32 v41, v40
	s_nop 0
	v_fma_f32 v44, -v40, v41, 1.0
	v_fmac_f32_e32 v41, v44, v41
	v_div_scale_f32 v44, vcc, v38, v39, v38
	v_mul_f32_e32 v46, v44, v41
	v_fma_f32 v48, -v40, v46, v44
	v_fmac_f32_e32 v46, v48, v41
	v_fma_f32 v40, -v40, v46, v44
	v_div_fmas_f32 v40, v40, v41, v46
	v_div_fixup_f32 v38, v40, v39, v38
	v_mul_f32_e32 v37, v38, v37
	v_cvt_pk_bf16_f32 v35, v36, v37
	global_store_dwordx2 v[60:61], v[34:35], off
	v_add_f32_e32 v34, 0, v45
	v_add_f32_e32 v34, v34, v47
	v_add_f32_e32 v34, v34, v49
	v_add_f32_e32 v34, v34, v51
	v_lshlrev_b32_e32 v37, 16, v76
	v_add_f32_e32 v34, v34, v53
	v_mul_f32_e32 v38, 0xbfb8aa3b, v37
	v_add_f32_e32 v34, v34, v55
	v_exp_f32_e32 v38, v38
	v_add_f32_e32 v34, v34, v57
	v_add_f32_e32 v34, v34, v59
	v_fmamk_f32 v34, v34, 0x3b800000, v203
	v_cmp_gt_f32_e32 vcc, s89, v34
	v_mul_f32_e32 v35, 0x4b800000, v34
	v_add_f32_e32 v38, 1.0, v38
	v_cndmask_b32_e32 v34, v34, v35, vcc
	v_div_scale_f32 v39, s[0:1], v38, v38, v37
	v_rsq_f32_e32 v34, v34
	v_rcp_f32_e32 v40, v39
	v_mul_f32_e32 v35, 0x45800000, v34
	v_fma_f32 v41, -v39, v40, 1.0
	v_cndmask_b32_e32 v36, v34, v35, vcc
	v_fmac_f32_e32 v40, v41, v40
	v_div_scale_f32 v41, vcc, v37, v38, v37
	v_mul_f32_e32 v44, v41, v40
	v_fma_f32 v45, -v39, v44, v41
	v_fmac_f32_e32 v44, v45, v40
	v_fma_f32 v39, -v39, v44, v41
	v_mul_f32_e32 v30, v30, v36
	v_div_fmas_f32 v39, v39, v40, v44
	v_mul_f32_e32 v30, v14, v30
	v_div_fixup_f32 v37, v39, v38, v37
	v_mul_f32_e32 v30, v37, v30
	v_and_b32_e32 v37, 0xffff0000, v76
	v_mul_f32_e32 v38, 0xbfb8aa3b, v37
	v_exp_f32_e32 v38, v38
	v_mul_f32_e32 v31, v31, v36
	v_mul_f32_e32 v31, v15, v31
	v_mul_f32_e32 v32, v32, v36
	v_add_f32_e32 v38, 1.0, v38
	v_div_scale_f32 v39, s[0:1], v38, v38, v37
	v_rcp_f32_e32 v40, v39
	v_mul_f32_e32 v32, v16, v32
	v_lshlrev_b64 v[34:35], 12, v[78:79]
	v_mul_f32_e32 v33, v33, v36
	v_fma_f32 v41, -v39, v40, 1.0
	v_fmac_f32_e32 v40, v41, v40
	v_div_scale_f32 v41, vcc, v37, v38, v37
	v_mul_f32_e32 v44, v41, v40
	v_fma_f32 v45, -v39, v44, v41
	v_fmac_f32_e32 v44, v45, v40
	v_fma_f32 v39, -v39, v44, v41
	v_div_fmas_f32 v39, v39, v40, v44
	v_div_fixup_f32 v37, v39, v38, v37
	v_mul_f32_e32 v31, v37, v31
	v_lshlrev_b32_e32 v37, 16, v77
	v_mul_f32_e32 v38, 0xbfb8aa3b, v37
	v_exp_f32_e32 v38, v38
	v_lshl_add_u64 v[34:35], v[42:43], 0, v[34:35]
	v_mul_f32_e32 v33, v17, v33
	v_cvt_pk_bf16_f32 v30, v30, v31
	v_add_f32_e32 v38, 1.0, v38
	v_div_scale_f32 v39, s[0:1], v38, v38, v37
	v_rcp_f32_e32 v40, v39
	v_mul_f32_e32 v26, v26, v36
	v_mul_f32_e32 v26, v6, v26
	v_mul_f32_e32 v27, v27, v36
	v_fma_f32 v41, -v39, v40, 1.0
	v_fmac_f32_e32 v40, v41, v40
	v_div_scale_f32 v41, vcc, v37, v38, v37
	v_mul_f32_e32 v44, v41, v40
	v_fma_f32 v45, -v39, v44, v41
	v_fmac_f32_e32 v44, v45, v40
	v_fma_f32 v39, -v39, v44, v41
	v_div_fmas_f32 v39, v39, v40, v44
	v_div_fixup_f32 v37, v39, v38, v37
	v_mul_f32_e32 v32, v37, v32
	v_and_b32_e32 v37, 0xffff0000, v77
	v_mul_f32_e32 v38, 0xbfb8aa3b, v37
	v_exp_f32_e32 v38, v38
	v_mul_f32_e32 v27, v7, v27
	v_mul_f32_e32 v28, v28, v36
	v_mul_f32_e32 v28, v8, v28
	v_add_f32_e32 v38, 1.0, v38
	v_div_scale_f32 v39, s[0:1], v38, v38, v37
	v_rcp_f32_e32 v40, v39
	v_mul_f32_e32 v29, v29, v36
	v_mul_f32_e32 v29, v9, v29
	v_fma_f32 v41, -v39, v40, 1.0
	v_fmac_f32_e32 v40, v41, v40
	v_div_scale_f32 v41, vcc, v37, v38, v37
	v_mul_f32_e32 v44, v41, v40
	v_fma_f32 v45, -v39, v44, v41
	v_fmac_f32_e32 v44, v45, v40
	v_fma_f32 v39, -v39, v44, v41
	v_div_fmas_f32 v39, v39, v40, v44
	v_div_fixup_f32 v37, v39, v38, v37
	v_mul_f32_e32 v33, v37, v33
	v_cvt_pk_bf16_f32 v31, v32, v33
	global_store_dwordx2 v[34:35], v[30:31], off offset:8
	v_lshlrev_b32_e32 v30, 16, v74
	v_mul_f32_e32 v31, 0xbfb8aa3b, v30
	v_exp_f32_e32 v31, v31
	ds_read2_b32 v[40:41], v0 offset0:224 offset1:240
	v_lshlrev_b64 v[44:45], 12, v[72:73]
	v_lshl_add_u64 v[44:45], v[42:43], 0, v[44:45]
	v_add_f32_e32 v31, 1.0, v31
	v_div_scale_f32 v32, s[0:1], v31, v31, v30
	v_rcp_f32_e32 v33, v32
	s_nop 0
	v_fma_f32 v37, -v32, v33, 1.0
	v_fmac_f32_e32 v33, v37, v33
	v_div_scale_f32 v37, vcc, v30, v31, v30
	v_mul_f32_e32 v38, v37, v33
	v_fma_f32 v39, -v32, v38, v37
	v_fmac_f32_e32 v38, v39, v33
	v_fma_f32 v32, -v32, v38, v37
	v_div_fmas_f32 v32, v32, v33, v38
	v_div_fixup_f32 v30, v32, v31, v30
	v_mul_f32_e32 v26, v30, v26
	v_and_b32_e32 v30, 0xffff0000, v74
	v_mul_f32_e32 v31, 0xbfb8aa3b, v30
	v_exp_f32_e32 v31, v31
	s_nop 0
	v_add_f32_e32 v31, 1.0, v31
	v_div_scale_f32 v32, s[0:1], v31, v31, v30
	v_rcp_f32_e32 v33, v32
	s_nop 0
	v_fma_f32 v37, -v32, v33, 1.0
	v_fmac_f32_e32 v33, v37, v33
	v_div_scale_f32 v37, vcc, v30, v31, v30
	v_mul_f32_e32 v38, v37, v33
	v_fma_f32 v39, -v32, v38, v37
	v_fmac_f32_e32 v38, v39, v33
	v_fma_f32 v32, -v32, v38, v37
	v_div_fmas_f32 v32, v32, v33, v38
	v_div_fixup_f32 v30, v32, v31, v30
	v_mul_f32_e32 v27, v30, v27
	v_lshlrev_b32_e32 v30, 16, v75
	v_mul_f32_e32 v31, 0xbfb8aa3b, v30
	v_exp_f32_e32 v31, v31
	v_cvt_pk_bf16_f32 v26, v26, v27
	s_nop 0
	v_add_f32_e32 v31, 1.0, v31
	v_div_scale_f32 v32, s[0:1], v31, v31, v30
	v_rcp_f32_e32 v33, v32
	s_nop 0
	v_fma_f32 v37, -v32, v33, 1.0
	v_fmac_f32_e32 v33, v37, v33
	v_div_scale_f32 v37, vcc, v30, v31, v30
	v_mul_f32_e32 v38, v37, v33
	v_fma_f32 v39, -v32, v38, v37
	v_fmac_f32_e32 v38, v39, v33
	v_fma_f32 v32, -v32, v38, v37
	v_div_fmas_f32 v32, v32, v33, v38
	v_div_fixup_f32 v30, v32, v31, v30
	v_mul_f32_e32 v28, v30, v28
	v_and_b32_e32 v30, 0xffff0000, v75
	v_mul_f32_e32 v31, 0xbfb8aa3b, v30
	v_exp_f32_e32 v31, v31
	s_nop 0
	v_add_f32_e32 v31, 1.0, v31
	v_div_scale_f32 v32, s[0:1], v31, v31, v30
	v_rcp_f32_e32 v33, v32
	s_nop 0
	v_fma_f32 v36, -v32, v33, 1.0
	v_fmac_f32_e32 v33, v36, v33
	v_div_scale_f32 v36, vcc, v30, v31, v30
	v_mul_f32_e32 v37, v36, v33
	v_fma_f32 v38, -v32, v37, v36
	v_fmac_f32_e32 v37, v38, v33
	v_fma_f32 v32, -v32, v37, v36
	v_div_fmas_f32 v32, v32, v33, v37
	v_div_fixup_f32 v30, v32, v31, v30
	v_mul_f32_e32 v29, v30, v29
	v_cvt_pk_bf16_f32 v27, v28, v29
	global_store_dwordx2 v[34:35], v[26:27], off
	ds_read2_b32 v[26:27], v86 offset0:32 offset1:48
	ds_read2_b32 v[28:29], v86 offset0:96 offset1:112
	ds_read2_b32 v[30:31], v86 offset0:160 offset1:176
	ds_read2_b32 v[32:33], v86 offset0:224 offset1:240
	ds_read2_b32 v[34:35], v0 offset0:32 offset1:48
	s_waitcnt lgkmcnt(4)
; __device__ __forceinline__ unsigned cvt_pk_bf16(float lo, float hi) { unsigned r; asm("v_cvt_pk_bf16_f32 %0, %1, %2" : "=v"(r) : "v"(lo), "v"(hi)); return r; }
; __device__ __forceinline__ float bflo(unsigned w) { return __uint_as_float(w << 16); }
; __device__ __forceinline__ float bfhi(unsigned w) { return __uint_as_float(w & 0xffff0000u); }
; __device__ __forceinline__ float silu(float x) { return x / (1.f + __expf(-x)); }
; template <bool SMP>
; __device__ __forceinline__ void gla_out_item(const Params& p, int l, int c, int h, LAS unsigned char* lds) {
;     ...
;     for (int mt = 0; mt < 4; ++mt) {
;         const int t = mt * 16 + fr;
;         float tot = 0.f;
; #pragma unroll
;         for (int ww = 0; ww < 8; ++ww) tot += red[ww * 64 + t];
;         const float rs = rsqrtf(tot * (1.f / 256.f) + EPS);
; #pragma unroll
;         for (int n = 0; n < 2; ++n) {
;             const f32x4 gg = n ? g1 : g0; const u32x2 ga = gav[mt][n];
;             const float o0 = o[mt][n][0] * rs * gg[0] * silu(bflo(ga.x)), o1 = o[mt][n][1] * rs * gg[1] * silu(bfhi(ga.x));
;             const float o2 = o[mt][n][2] * rs * gg[2] * silu(bflo(ga.y)), o3 = o[mt][n][3] * rs * gg[3] * silu(bfhi(ga.y));
;             u32x2 wv; wv.x = cvt_pk_bf16(o0, o1); wv.y = cvt_pk_bf16(o2, o3);
;             *(u32x2*)((u16*)(ws + WS_OBUF) + (size_t)(tok0 + t) * 2048 + h * 256 + w * 32 + n * 16 + fq * 4) = wv;
;         }
	v_add_f32_e32 v26, 0, v26
	ds_read2_b32 v[36:37], v0 offset0:96 offset1:112
	s_waitcnt lgkmcnt(4)
	v_add_f32_e32 v26, v26, v28
	ds_read2_b32 v[38:39], v0 offset0:160 offset1:176
	s_waitcnt lgkmcnt(4)
	v_add_f32_e32 v26, v26, v30
	s_waitcnt lgkmcnt(3)
	v_add_f32_e32 v26, v26, v32
	s_waitcnt lgkmcnt(2)
	v_add_f32_e32 v26, v26, v34
	s_waitcnt lgkmcnt(1)
	v_add_f32_e32 v26, v26, v36
	s_waitcnt lgkmcnt(0)
	v_add_f32_e32 v26, v26, v38
	v_add_f32_e32 v0, v26, v40
	v_fmamk_f32 v0, v0, 0x3b800000, v203
	v_cmp_gt_f32_e32 vcc, s89, v0
	v_mul_f32_e32 v26, 0x4b800000, v0
	s_nop 0
	v_cndmask_b32_e32 v0, v0, v26, vcc
	v_rsq_f32_e32 v0, v0
	s_nop 0
	v_mul_f32_e32 v26, 0x45800000, v0
	v_cndmask_b32_e32 v0, v0, v26, vcc
	v_lshlrev_b32_e32 v26, 16, v70
	v_mul_f32_e32 v28, 0xbfb8aa3b, v26
	v_exp_f32_e32 v28, v28
	v_mul_f32_e32 v22, v22, v0
	v_mul_f32_e32 v22, v14, v22
	v_mul_f32_e32 v23, v23, v0
	v_add_f32_e32 v28, 1.0, v28
	v_div_scale_f32 v30, s[0:1], v28, v28, v26
	v_rcp_f32_e32 v32, v30
	v_mul_f32_e32 v23, v15, v23
	v_mul_f32_e32 v24, v24, v0
	v_mul_f32_e32 v24, v16, v24
	v_fma_f32 v34, -v30, v32, 1.0
	v_fmac_f32_e32 v32, v34, v32
	v_div_scale_f32 v34, vcc, v26, v28, v26
	v_mul_f32_e32 v36, v34, v32
	v_fma_f32 v38, -v30, v36, v34
	v_fmac_f32_e32 v36, v38, v32
	v_fma_f32 v30, -v30, v36, v34
	v_div_fmas_f32 v30, v30, v32, v36
	v_div_fixup_f32 v26, v30, v28, v26
	v_mul_f32_e32 v22, v26, v22
	v_and_b32_e32 v26, 0xffff0000, v70
	v_mul_f32_e32 v28, 0xbfb8aa3b, v26
	v_exp_f32_e32 v28, v28
	v_mul_f32_e32 v25, v25, v0
	v_mul_f32_e32 v25, v17, v25
	v_mul_f32_e32 v18, v18, v0
	v_add_f32_e32 v28, 1.0, v28
	v_div_scale_f32 v30, s[0:1], v28, v28, v26
	v_rcp_f32_e32 v32, v30
	v_mul_f32_e32 v18, v6, v18
	v_mul_f32_e32 v19, v19, v0
	v_mul_f32_e32 v19, v7, v19
	v_fma_f32 v34, -v30, v32, 1.0
	v_fmac_f32_e32 v32, v34, v32
	v_div_scale_f32 v34, vcc, v26, v28, v26
	v_mul_f32_e32 v36, v34, v32
	v_fma_f32 v38, -v30, v36, v34
	v_fmac_f32_e32 v36, v38, v32
	v_fma_f32 v30, -v30, v36, v34
	v_div_fmas_f32 v30, v30, v32, v36
	v_div_fixup_f32 v26, v30, v28, v26
	v_mul_f32_e32 v23, v26, v23
	v_lshlrev_b32_e32 v26, 16, v71
	v_mul_f32_e32 v28, 0xbfb8aa3b, v26
	v_exp_f32_e32 v28, v28
	v_cvt_pk_bf16_f32 v22, v22, v23
	v_mul_f32_e32 v20, v20, v0
	v_mul_f32_e32 v20, v8, v20
	v_add_f32_e32 v28, 1.0, v28
	v_div_scale_f32 v30, s[0:1], v28, v28, v26
	v_rcp_f32_e32 v32, v30
	v_mul_f32_e32 v0, v21, v0
	v_and_b32_e32 v21, 0xffff0000, v69
	v_mul_f32_e32 v0, v9, v0
	v_fma_f32 v34, -v30, v32, 1.0
	v_fmac_f32_e32 v32, v34, v32
	v_div_scale_f32 v34, vcc, v26, v28, v26
	v_mul_f32_e32 v36, v34, v32
	v_fma_f32 v38, -v30, v36, v34
	v_fmac_f32_e32 v36, v38, v32
	v_fma_f32 v30, -v30, v36, v34
	v_div_fmas_f32 v30, v30, v32, v36
	v_div_fixup_f32 v26, v30, v28, v26
	v_mul_f32_e32 v24, v26, v24
	v_and_b32_e32 v26, 0xffff0000, v71
	v_mul_f32_e32 v28, 0xbfb8aa3b, v26
	v_exp_f32_e32 v28, v28
	s_nop 0
	v_add_f32_e32 v28, 1.0, v28
	v_div_scale_f32 v30, s[0:1], v28, v28, v26
	v_rcp_f32_e32 v32, v30
	s_nop 0
	v_fma_f32 v34, -v30, v32, 1.0
	v_fmac_f32_e32 v32, v34, v32
	v_div_scale_f32 v34, vcc, v26, v28, v26
	v_mul_f32_e32 v36, v34, v32
	v_fma_f32 v38, -v30, v36, v34
	v_fmac_f32_e32 v36, v38, v32
	v_fma_f32 v30, -v30, v36, v34
	v_div_fmas_f32 v30, v30, v32, v36
	v_div_fixup_f32 v26, v30, v28, v26
	v_mul_f32_e32 v25, v26, v25
	v_cvt_pk_bf16_f32 v23, v24, v25
	global_store_dwordx2 v[44:45], v[22:23], off offset:8
	v_lshlrev_b32_e32 v22, 16, v68
	v_mul_f32_e32 v23, 0xbfb8aa3b, v22
	v_exp_f32_e32 v23, v23
	s_nop 0
	v_add_f32_e32 v23, 1.0, v23
	v_div_scale_f32 v24, s[0:1], v23, v23, v22
	v_rcp_f32_e32 v25, v24
	s_nop 0
	v_fma_f32 v26, -v24, v25, 1.0
	v_fmac_f32_e32 v25, v26, v25
	v_div_scale_f32 v26, vcc, v22, v23, v22
	v_mul_f32_e32 v28, v26, v25
	v_fma_f32 v30, -v24, v28, v26
	v_fmac_f32_e32 v28, v30, v25
	v_fma_f32 v24, -v24, v28, v26
	v_div_fmas_f32 v24, v24, v25, v28
	v_div_fixup_f32 v22, v24, v23, v22
	v_mul_f32_e32 v18, v22, v18
	v_and_b32_e32 v22, 0xffff0000, v68
	v_mul_f32_e32 v23, 0xbfb8aa3b, v22
	v_exp_f32_e32 v23, v23
	s_nop 0
	v_add_f32_e32 v23, 1.0, v23
	v_div_scale_f32 v24, s[0:1], v23, v23, v22
	v_rcp_f32_e32 v25, v24
	s_nop 0
	v_fma_f32 v26, -v24, v25, 1.0
	v_fmac_f32_e32 v25, v26, v25
	v_div_scale_f32 v26, vcc, v22, v23, v22
	v_mul_f32_e32 v28, v26, v25
	v_fma_f32 v30, -v24, v28, v26
	v_fmac_f32_e32 v28, v30, v25
	v_fma_f32 v24, -v24, v28, v26
	v_div_fmas_f32 v24, v24, v25, v28
	v_div_fixup_f32 v22, v24, v23, v22
	v_mul_f32_e32 v19, v22, v19
	v_lshlrev_b32_e32 v22, 16, v69
	v_mul_f32_e32 v23, 0xbfb8aa3b, v22
	v_exp_f32_e32 v23, v23
	v_cvt_pk_bf16_f32 v18, v18, v19
	s_nop 0
	v_add_f32_e32 v23, 1.0, v23
	v_div_scale_f32 v24, s[0:1], v23, v23, v22
	v_rcp_f32_e32 v25, v24
	s_nop 0
	v_fma_f32 v26, -v24, v25, 1.0
	v_fmac_f32_e32 v25, v26, v25
	v_div_scale_f32 v26, vcc, v22, v23, v22
	v_mul_f32_e32 v28, v26, v25
	v_fma_f32 v30, -v24, v28, v26
	v_fmac_f32_e32 v28, v30, v25
	v_fma_f32 v24, -v24, v28, v26
	v_div_fmas_f32 v24, v24, v25, v28
	v_div_fixup_f32 v22, v24, v23, v22
	v_mul_f32_e32 v20, v22, v20
	v_mul_f32_e32 v22, 0xbfb8aa3b, v21
	v_exp_f32_e32 v22, v22
	s_nop 0
	v_add_f32_e32 v22, 1.0, v22
	v_div_scale_f32 v23, s[0:1], v22, v22, v21
	v_rcp_f32_e32 v24, v23
	s_nop 0
	v_fma_f32 v25, -v23, v24, 1.0
	v_fmac_f32_e32 v24, v25, v24
	v_div_scale_f32 v25, vcc, v21, v22, v21
	v_mul_f32_e32 v26, v25, v24
	v_fma_f32 v28, -v23, v26, v25
	v_fmac_f32_e32 v26, v28, v24
	v_fma_f32 v23, -v23, v26, v25
	v_div_fmas_f32 v23, v23, v24, v26
; __device__ __forceinline__ unsigned cvt_pk_bf16(float lo, float hi) { unsigned r; asm("v_cvt_pk_bf16_f32 %0, %1, %2" : "=v"(r) : "v"(lo), "v"(hi)); return r; }
; __device__ __forceinline__ float bflo(unsigned w) { return __uint_as_float(w << 16); }
; __device__ __forceinline__ float bfhi(unsigned w) { return __uint_as_float(w & 0xffff0000u); }
; __device__ __forceinline__ float silu(float x) { return x / (1.f + __expf(-x)); }
; template <bool SMP>
; __device__ __forceinline__ void gla_out_item(const Params& p, int l, int c, int h, LAS unsigned char* lds) {
;     ...
;     for (int mt = 0; mt < 4; ++mt) {
;         const int t = mt * 16 + fr;
;         float tot = 0.f;
; #pragma unroll
;         for (int ww = 0; ww < 8; ++ww) tot += red[ww * 64 + t];
;         const float rs = rsqrtf(tot * (1.f / 256.f) + EPS);
; #pragma unroll
;         for (int n = 0; n < 2; ++n) {
;             const f32x4 gg = n ? g1 : g0; const u32x2 ga = gav[mt][n];
;             const float o0 = o[mt][n][0] * rs * gg[0] * silu(bflo(ga.x)), o1 = o[mt][n][1] * rs * gg[1] * silu(bfhi(ga.x));
;             const float o2 = o[mt][n][2] * rs * gg[2] * silu(bflo(ga.y)), o3 = o[mt][n][3] * rs * gg[3] * silu(bfhi(ga.y));
;             u32x2 wv; wv.x = cvt_pk_bf16(o0, o1); wv.y = cvt_pk_bf16(o2, o3);
;             *(u32x2*)((u16*)(ws + WS_OBUF) + (size_t)(tok0 + t) * 2048 + h * 256 + w * 32 + n * 16 + fq * 4) = wv;
;         }
	v_div_fixup_f32 v21, v23, v22, v21
	v_mul_f32_e32 v0, v21, v0
	v_cvt_pk_bf16_f32 v19, v20, v0
	v_add_f32_e32 v0, 0, v27
	v_add_f32_e32 v0, v0, v29
	v_add_f32_e32 v0, v0, v31
	v_add_f32_e32 v0, v0, v33
	v_add_f32_e32 v0, v0, v35
	v_add_f32_e32 v0, v0, v37
	v_add_f32_e32 v0, v0, v39
	v_add_f32_e32 v0, v0, v41
	v_fmamk_f32 v0, v0, 0x3b800000, v203
	global_store_dwordx2 v[44:45], v[18:19], off
	v_cmp_gt_f32_e32 vcc, s89, v0
	v_mul_f32_e32 v18, 0x4b800000, v0
	s_nop 0
	v_cndmask_b32_e32 v0, v0, v18, vcc
	v_rsq_f32_e32 v0, v0
	s_nop 0
	v_mul_f32_e32 v18, 0x45800000, v0
	v_cndmask_b32_e32 v0, v0, v18, vcc
	v_mul_f32_e32 v10, v10, v0
	v_mul_f32_e32 v10, v14, v10
	v_lshlrev_b32_e32 v14, 16, v64
	v_mul_f32_e32 v20, 0xbfb8aa3b, v14
	v_exp_f32_e32 v20, v20
	v_mul_f32_e32 v11, v11, v0
	v_mul_f32_e32 v11, v15, v11
	v_mul_f32_e32 v12, v12, v0
	v_add_f32_e32 v20, 1.0, v20
	v_div_scale_f32 v21, s[0:1], v20, v20, v14
	v_rcp_f32_e32 v22, v21
	v_mul_f32_e32 v12, v16, v12
	v_mul_f32_e32 v13, v13, v0
	v_mul_f32_e32 v13, v17, v13
	v_fma_f32 v23, -v21, v22, 1.0
	v_fmac_f32_e32 v22, v23, v22
	v_div_scale_f32 v23, vcc, v14, v20, v14
	v_mul_f32_e32 v24, v23, v22
	v_fma_f32 v25, -v21, v24, v23
	v_fmac_f32_e32 v24, v25, v22
	v_fma_f32 v21, -v21, v24, v23
	v_div_fmas_f32 v21, v21, v22, v24
	v_div_fixup_f32 v14, v21, v20, v14
	v_mul_f32_e32 v10, v14, v10
	v_and_b32_e32 v14, 0xffff0000, v64
	v_mul_f32_e32 v15, 0xbfb8aa3b, v14
	v_exp_f32_e32 v15, v15
	v_lshlrev_b64 v[18:19], 12, v[66:67]
	v_mul_f32_e32 v2, v2, v0
	v_lshl_add_u64 v[18:19], v[42:43], 0, v[18:19]
	v_add_f32_e32 v15, 1.0, v15
	v_div_scale_f32 v20, s[0:1], v15, v15, v14
	v_rcp_f32_e32 v21, v20
	v_mul_f32_e32 v2, v6, v2
	v_lshlrev_b32_e32 v6, 16, v62
	v_mul_f32_e32 v3, v3, v0
	v_fma_f32 v22, -v20, v21, 1.0
	v_fmac_f32_e32 v21, v22, v21
	v_div_scale_f32 v22, vcc, v14, v15, v14
	v_mul_f32_e32 v23, v22, v21
	v_fma_f32 v24, -v20, v23, v22
	v_fmac_f32_e32 v23, v24, v21
	v_fma_f32 v20, -v20, v23, v22
	v_div_fmas_f32 v20, v20, v21, v23
	v_div_fixup_f32 v14, v20, v15, v14
	v_mul_f32_e32 v11, v14, v11
	v_lshlrev_b32_e32 v14, 16, v65
	v_mul_f32_e32 v15, 0xbfb8aa3b, v14
	v_exp_f32_e32 v15, v15
	v_cvt_pk_bf16_f32 v10, v10, v11
	v_mul_f32_e32 v3, v7, v3
	v_mul_f32_e32 v4, v4, v0
	v_add_f32_e32 v15, 1.0, v15
	v_div_scale_f32 v16, s[0:1], v15, v15, v14
	v_rcp_f32_e32 v20, v16
	v_mul_f32_e32 v4, v8, v4
	v_mul_f32_e32 v0, v5, v0
	v_and_b32_e32 v5, 0xffff0000, v63
	v_fma_f32 v21, -v16, v20, 1.0
	v_fmac_f32_e32 v20, v21, v20
	v_div_scale_f32 v21, vcc, v14, v15, v14
	v_mul_f32_e32 v22, v21, v20
	v_fma_f32 v23, -v16, v22, v21
	v_fmac_f32_e32 v22, v23, v20
	v_fma_f32 v16, -v16, v22, v21
	v_div_fmas_f32 v16, v16, v20, v22
	v_div_fixup_f32 v14, v16, v15, v14
	v_mul_f32_e32 v12, v14, v12
	v_and_b32_e32 v14, 0xffff0000, v65
	v_mul_f32_e32 v15, 0xbfb8aa3b, v14
	v_exp_f32_e32 v15, v15
	v_mul_f32_e32 v0, v9, v0
	v_add_f32_e32 v15, 1.0, v15
	v_div_scale_f32 v16, s[0:1], v15, v15, v14
	v_rcp_f32_e32 v17, v16
	s_nop 0
	v_fma_f32 v20, -v16, v17, 1.0
	v_fmac_f32_e32 v17, v20, v17
	v_div_scale_f32 v20, vcc, v14, v15, v14
	v_mul_f32_e32 v21, v20, v17
	v_fma_f32 v22, -v16, v21, v20
	v_fmac_f32_e32 v21, v22, v17
	v_fma_f32 v16, -v16, v21, v20
	v_div_fmas_f32 v16, v16, v17, v21
	v_div_fixup_f32 v14, v16, v15, v14
	v_mul_f32_e32 v13, v14, v13
	v_cvt_pk_bf16_f32 v11, v12, v13
	global_store_dwordx2 v[18:19], v[10:11], off offset:8
	v_mul_f32_e32 v10, 0xbfb8aa3b, v6
	v_exp_f32_e32 v10, v10
	s_nop 0
	v_add_f32_e32 v10, 1.0, v10
	v_div_scale_f32 v11, s[0:1], v10, v10, v6
	v_rcp_f32_e32 v12, v11
	s_nop 0
	v_fma_f32 v13, -v11, v12, 1.0
	v_fmac_f32_e32 v12, v13, v12
	v_div_scale_f32 v13, vcc, v6, v10, v6
	v_mul_f32_e32 v14, v13, v12
	v_fma_f32 v15, -v11, v14, v13
	v_fmac_f32_e32 v14, v15, v12
	v_fma_f32 v11, -v11, v14, v13
	v_div_fmas_f32 v11, v11, v12, v14
	v_div_fixup_f32 v6, v11, v10, v6
	v_mul_f32_e32 v2, v6, v2
	v_and_b32_e32 v6, 0xffff0000, v62
	v_mul_f32_e32 v7, 0xbfb8aa3b, v6
	v_exp_f32_e32 v7, v7
	s_nop 0
	v_add_f32_e32 v7, 1.0, v7
	v_div_scale_f32 v10, s[0:1], v7, v7, v6
	v_rcp_f32_e32 v11, v10
	s_nop 0
	v_fma_f32 v12, -v10, v11, 1.0
	v_fmac_f32_e32 v11, v12, v11
	v_div_scale_f32 v12, vcc, v6, v7, v6
	v_mul_f32_e32 v13, v12, v11
	v_fma_f32 v14, -v10, v13, v12
	v_fmac_f32_e32 v13, v14, v11
	v_fma_f32 v10, -v10, v13, v12
	v_div_fmas_f32 v10, v10, v11, v13
	v_div_fixup_f32 v6, v10, v7, v6
	v_mul_f32_e32 v3, v6, v3
	v_lshlrev_b32_e32 v6, 16, v63
	v_mul_f32_e32 v7, 0xbfb8aa3b, v6
	v_exp_f32_e32 v7, v7
	v_cvt_pk_bf16_f32 v2, v2, v3
	s_nop 0
	v_add_f32_e32 v7, 1.0, v7
	v_div_scale_f32 v8, s[0:1], v7, v7, v6
	v_rcp_f32_e32 v10, v8
	s_nop 0
	v_fma_f32 v11, -v8, v10, 1.0
	v_fmac_f32_e32 v10, v11, v10
	v_div_scale_f32 v11, vcc, v6, v7, v6
	v_mul_f32_e32 v12, v11, v10
	v_fma_f32 v13, -v8, v12, v11
	v_fmac_f32_e32 v12, v13, v10
	v_fma_f32 v8, -v8, v12, v11
	v_div_fmas_f32 v8, v8, v10, v12
	v_div_fixup_f32 v6, v8, v7, v6
	v_mul_f32_e32 v4, v6, v4
	v_mul_f32_e32 v6, 0xbfb8aa3b, v5
	v_exp_f32_e32 v6, v6
	s_nop 0
	v_add_f32_e32 v6, 1.0, v6
	v_div_scale_f32 v7, s[0:1], v6, v6, v5
	v_rcp_f32_e32 v8, v7
	s_mov_b64 s[0:1], 0
	v_fma_f32 v9, -v7, v8, 1.0
	v_fmac_f32_e32 v8, v9, v8
	v_div_scale_f32 v9, vcc, v5, v6, v5
	v_mul_f32_e32 v10, v9, v8
	v_fma_f32 v11, -v7, v10, v9
	v_fmac_f32_e32 v10, v11, v8
	v_fma_f32 v7, -v7, v10, v9
	v_div_fmas_f32 v7, v7, v8, v10
	v_div_fixup_f32 v5, v7, v6, v5
	v_mul_f32_e32 v0, v5, v0
	v_cvt_pk_bf16_f32 v3, v4, v0
	global_store_dwordx2 v[18:19], v[2:3], off
	s_barrier
